# differential attention unit prologue de-serialised: first-stage K/V loads issued before the Q-norm wait ladder (ladder waits +8) so the two memory latencies overlap (on v103)
# speedup vs baseline: 1.0020x; 1.0020x over previous
.LBB0_298:
	s_or_b64 exec, exec, s[4:5]
	v_mov_b32_e32 v1, s33
	s_waitcnt lgkmcnt(0)
	s_barrier
	ds_read_b32 v1, v1
	s_movk_i32 s4, 0x43f
	s_waitcnt lgkmcnt(0)
	v_cmp_lt_i32_e32 vcc, s4, v1
	v_readfirstlane_b32 s6, v1
	s_mov_b64 s[4:5], -1
	s_cbranch_vccnz .LBB0_293
	s_and_b32 s16, s6, 15
	s_bfe_u32 s4, s6, 0x20004
	s_lshl_b32 s7, s16, 4
	v_readlane_b32 s8, v254, 43
	s_lshl_b32 s6, s6, 1
	s_or_b32 s7, s7, s8
	s_and_b32 s8, s6, 0xffffff80
	v_mov_b32_e32 v187, v202
	s_sub_i32 s37, 0x800, s8
	s_add_i32 s54, s37, s63
	v_and_b32_e32 v186, 31, v187
	v_or_b32_e32 v2, s54, v186
	s_mulk_i32 s4, 0x810
	s_mov_b32 s5, s89
	v_ashrrev_i32_e32 v3, 31, v2
	v_lshl_add_u64 v[6:7], v[2:3], 0, s[4:5]
	v_mov_b32_e32 v1, s7
	v_lshlrev_b64 v[6:7], 13, v[6:7]
	v_readlane_b32 s6, v254, 48
	v_ashrrev_i32_e32 v201, 5, v187
	v_lshl_add_u64 v[6:7], s[10:11], 0, v[6:7]
	s_lshl_b32 s88, s16, 8
	v_readlane_b32 s7, v254, 49
	v_lshl_add_u64 v[6:7], v[6:7], 0, s[88:89]
	s_mov_b32 s7, s89
	v_lshlrev_b32_e32 v188, 3, v201
	v_lshl_add_u64 v[6:7], v[6:7], 0, s[6:7]
	v_ashrrev_i32_e32 v189, 31, v188
	v_lshl_add_u64 v[6:7], v[188:189], 1, v[6:7]
	global_load_dwordx2 v[4:5], v1, s[76:77] offset:2048
	global_load_dwordx4 v[116:119], v[6:7], off
	global_load_dwordx4 v[120:123], v[6:7], off offset:32
	global_load_dwordx4 v[124:127], v[6:7], off offset:64
	global_load_dwordx4 v[128:131], v[6:7], off offset:96
	s_mov_b32 s38, s6
	v_writelane_b32 v254, s38, 48
	s_lshl_b32 s9, s16, 7
	v_writelane_b32 v254, s39, 49
	s_mov_b64 s[6:7], exec
	v_readlane_b32 s38, v254, 51
	v_readlane_b32 s39, v254, 52
	s_and_b64 s[38:39], s[6:7], s[38:39]
	s_mov_b64 exec, s[38:39]
	ds_write_b32 v203, v0
	s_or_b64 exec, exec, s[6:7]
	s_add_i32 s5, s54, -16
	s_lshr_b32 s6, s54, 6
	s_add_i32 s42, s16, 1
	s_lshr_b32 s5, s5, 6
	s_add_i32 s6, s6, 1
	s_cmp_gt_i32 s54, -1
	s_cselect_b32 s6, s6, 0
	s_lshl_b32 s7, s6, 6
	s_lshl_b32 s6, s6, 1
	s_cmpk_lt_u32 s7, 0x880
	s_cselect_b32 s55, s6, 0x43
	s_sub_i32 s6, 0x900, s8
	s_lshr_b32 s6, s6, 7
	s_add_i32 s38, s6, -1
	v_lshrrev_b32_e32 v6, 3, v164
	v_or_b32_e32 v8, s9, v165
	s_lshl_b32 s88, s4, 1
	v_add_lshl_u32 v6, s4, v6, 13
	v_mov_b32_e32 v7, v0
	v_mul_u32_u24_e32 v8, 0x2200, v8
	s_cmp_gt_i32 s54, 15
	v_lshl_add_u64 v[6:7], s[10:11], 0, v[6:7]
	v_lshlrev_b32_e32 v8, 1, v8
	v_mov_b32_e32 v9, v0
	s_cselect_b64 s[16:17], -1, 0
	s_lshl_b32 s6, s9, 1
	s_mov_b32 s7, s89
	v_lshl_add_u64 v[8:9], s[86:87], 0, v[8:9]
	s_cmpk_lt_u32 s37, 0x800
	v_lshl_add_u64 v[6:7], v[6:7], 0, s[6:7]
	v_mov_b32_e32 v169, v0
	v_lshl_add_u64 v[8:9], v[8:9], 0, s[88:89]
	s_cselect_b32 s88, s38, 16
	v_lshl_add_u64 v[6:7], v[6:7], 0, v[168:169]
	s_mov_b64 s[38:39], 0x1000
	v_mov_b32_e32 v167, v0
	v_lshl_add_u64 v[192:193], v[6:7], 0, s[38:39]
	s_lshl_b64 s[38:39], s[88:89], 20
	v_lshl_add_u64 v[190:191], v[8:9], 0, v[166:167]
	v_lshl_add_u64 v[6:7], v[192:193], 0, s[38:39]
	s_mov_b64 s[40:41], 0x88000
	v_add_co_u32_e32 v8, vcc, s24, v6
	s_lshl_b64 s[38:39], s[88:89], 8
	v_lshl_add_u64 v[194:195], v[190:191], 0, s[40:41]
	s_mov_b64 s[40:41], 0x110000
	v_addc_co_u32_e32 v9, vcc, 0, v7, vcc
	global_load_dwordx4 v[132:135], v[6:7], off
	global_load_dwordx4 v[136:139], v[6:7], off offset:128
	global_load_dwordx4 v[140:143], v[8:9], off
	global_load_dwordx4 v[144:147], v[8:9], off offset:128
	v_lshl_add_u64 v[6:7], v[190:191], 0, s[38:39]
	v_lshl_add_u64 v[196:197], v[190:191], 0, s[40:41]
	s_mov_b64 s[40:41], 0x198000
	v_lshl_add_u64 v[8:9], v[194:195], 0, s[38:39]
	global_load_dwordx4 v[148:151], v[6:7], off
	global_load_dwordx4 v[152:155], v[8:9], off
	v_lshl_add_u64 v[6:7], v[196:197], 0, s[38:39]
	v_lshl_add_u64 v[198:199], v[190:191], 0, s[40:41]
	v_lshl_add_u64 v[8:9], v[198:199], 0, s[38:39]
	global_load_dwordx4 v[156:159], v[6:7], off
	global_load_dwordx4 v[160:163], v[8:9], off
	s_waitcnt vmcnt(11)
	v_and_b32_e32 v1, 0xffff0000, v116
	v_lshlrev_b32_e32 v3, 16, v116
	v_mul_f32_e32 v1, v1, v1
	v_fmac_f32_e32 v1, v3, v3
	v_lshlrev_b32_e32 v3, 16, v117
	v_fmac_f32_e32 v1, v3, v3
	v_and_b32_e32 v3, 0xffff0000, v117
	v_fmac_f32_e32 v1, v3, v3
	v_lshlrev_b32_e32 v3, 16, v118
	v_fmac_f32_e32 v1, v3, v3
	v_and_b32_e32 v3, 0xffff0000, v118
	v_fmac_f32_e32 v1, v3, v3
	v_lshlrev_b32_e32 v3, 16, v119
	v_fmac_f32_e32 v1, v3, v3
	v_and_b32_e32 v3, 0xffff0000, v119
	v_fmac_f32_e32 v1, v3, v3
	s_waitcnt vmcnt(10)
	v_lshlrev_b32_e32 v3, 16, v120
	v_fmac_f32_e32 v1, v3, v3
	v_and_b32_e32 v3, 0xffff0000, v120
	v_fmac_f32_e32 v1, v3, v3
	v_lshlrev_b32_e32 v3, 16, v121
	v_fmac_f32_e32 v1, v3, v3
	v_and_b32_e32 v3, 0xffff0000, v121
	v_fmac_f32_e32 v1, v3, v3
	v_lshlrev_b32_e32 v3, 16, v122
	v_fmac_f32_e32 v1, v3, v3
	v_and_b32_e32 v3, 0xffff0000, v122
	v_fmac_f32_e32 v1, v3, v3
	v_lshlrev_b32_e32 v3, 16, v123
	v_fmac_f32_e32 v1, v3, v3
	v_and_b32_e32 v3, 0xffff0000, v123
	v_fmac_f32_e32 v1, v3, v3
	s_waitcnt vmcnt(9)
	v_lshlrev_b32_e32 v3, 16, v124
	v_fmac_f32_e32 v1, v3, v3
	v_and_b32_e32 v3, 0xffff0000, v124
	v_fmac_f32_e32 v1, v3, v3
	v_lshlrev_b32_e32 v3, 16, v125
	v_fmac_f32_e32 v1, v3, v3
	v_and_b32_e32 v3, 0xffff0000, v125
	v_fmac_f32_e32 v1, v3, v3
	v_lshlrev_b32_e32 v3, 16, v126
	v_fmac_f32_e32 v1, v3, v3
	v_and_b32_e32 v3, 0xffff0000, v126
	v_fmac_f32_e32 v1, v3, v3
	v_lshlrev_b32_e32 v3, 16, v127
	v_fmac_f32_e32 v1, v3, v3
	v_and_b32_e32 v3, 0xffff0000, v127
	v_fmac_f32_e32 v1, v3, v3
	s_waitcnt vmcnt(8)
	v_lshlrev_b32_e32 v3, 16, v128
	v_fmac_f32_e32 v1, v3, v3
	v_and_b32_e32 v3, 0xffff0000, v128
	v_fmac_f32_e32 v1, v3, v3
	v_lshlrev_b32_e32 v3, 16, v129
	v_fmac_f32_e32 v1, v3, v3
	v_and_b32_e32 v3, 0xffff0000, v129
	v_fmac_f32_e32 v1, v3, v3
	v_lshlrev_b32_e32 v3, 16, v130
	v_fmac_f32_e32 v1, v3, v3
	v_and_b32_e32 v3, 0xffff0000, v130
	v_fmac_f32_e32 v1, v3, v3
	v_lshlrev_b32_e32 v3, 16, v131
	v_fmac_f32_e32 v1, v3, v3
	v_and_b32_e32 v3, 0xffff0000, v131
	v_fmac_f32_e32 v1, v3, v3
	ds_bpermute_b32 v3, v200, v1
	v_add_f32_e32 v4, v4, v5
	s_waitcnt lgkmcnt(0)
	v_add_f32_e32 v1, v1, v3
	v_mul_f32_e32 v1, v4, v1
	s_mov_b32 s9, 0xf800000
	v_add_u32_e32 v5, -16, v2
	v_mul_f32_e32 v3, 0x4f800000, v1
	v_cmp_gt_f32_e32 vcc, s9, v1
	v_lshrrev_b32_e32 v167, 6, v5
	v_cvt_f32_ubyte0_e32 v5, s42
	v_cndmask_b32_e32 v1, v1, v3, vcc
	v_mul_f32_e32 v5, -0.5, v5
	v_sqrt_f32_e32 v3, v1
	v_exp_f32_e32 v5, v5
	s_lshl_b32 s57, s88, 16
	s_and_b32 s9, s57, 0x10000
	v_add_u32_e32 v4, -1, v3
	v_mul_f32_e32 v214, 0xbfb8aa3b, v5
	v_fma_f32 v5, -v4, v3, v1
	v_cmp_ge_f32_e64 s[40:41], 0, v5
	v_add_u32_e32 v5, 1, v3
	v_lshlrev_b32_e32 v6, 1, v186
	v_cndmask_b32_e64 v4, v3, v4, s[40:41]
	v_fma_f32 v3, -v5, v3, v1
	v_cmp_lt_f32_e64 s[40:41], 0, v3
	v_lshrrev_b32_e32 v7, 1, v187
	v_and_b32_e32 v6, 8, v6
	v_cndmask_b32_e64 v3, v4, v5, s[40:41]
	v_mul_f32_e32 v4, 0x37800000, v3
	v_cndmask_b32_e32 v3, v3, v4, vcc
	v_mov_b32_e32 v4, 0x260
	v_cmp_class_f32_e32 vcc, v1, v4
	v_and_b32_e32 v7, 4, v7
	v_and_b32_e32 v8, 19, v187
	v_cndmask_b32_e32 v1, v3, v1, vcc
	v_mul_f32_e32 v1, 0x3e38aa3b, v1
	v_fmamk_f32 v215, v1, 0x3f8020c5, v208
	v_add_u32_e32 v1, s9, v204
	v_or3_b32 v6, v7, v8, v6
	v_lshrrev_b32_e32 v7, 1, v6
	v_cmp_gt_i32_e64 s[38:39], 16, v2
	s_waitcnt vmcnt(7)
	ds_write_b128 v1, v[132:135]
	s_waitcnt vmcnt(5)
	ds_write_b128 v1, v[140:143] offset:8192
	ds_write_b128 v1, v[136:139] offset:16384
	s_waitcnt vmcnt(4)
	ds_write_b128 v1, v[144:147] offset:24576
	s_waitcnt vmcnt(3)
	ds_write_b128 v1, v[148:151] offset:32768
	s_waitcnt vmcnt(2)
	ds_write_b128 v1, v[152:155] offset:40960
	s_waitcnt vmcnt(1)
	ds_write_b128 v1, v[156:159] offset:49152
	s_waitcnt vmcnt(0)
	ds_write_b128 v1, v[160:163] offset:57344
	v_cvt_f32_i32_e32 v1, v2
	v_bitop3_b32 v2, v7, v201, 7 bitop3:0x6c
	v_lshlrev_b32_e32 v232, 4, v2
	v_readlane_b32 s42, v254, 45
	v_mul_f32_e64 v231, -v214, v1
	v_add_u32_e32 v1, 2, v201
	v_bitop3_b32 v2, v7, v1, 7 bitop3:0x6c
	v_lshlrev_b32_e32 v233, 4, v2
	v_add_u32_e32 v2, 4, v201
	v_bitop3_b32 v3, v7, v2, 7 bitop3:0x6c
	v_lshlrev_b32_e32 v234, 4, v3
	v_add_u32_e32 v3, 6, v201
	v_bitop3_b32 v4, v7, v3, 7 bitop3:0x6c
	v_lshlrev_b32_e32 v235, 4, v4
	v_add_u32_e32 v4, 12, v201
	v_bitop3_b32 v4, v4, v187, 15 bitop3:0x78
	v_lshlrev_b32_e32 v236, 4, v4
	v_add_u32_e32 v4, 14, v201
	v_bitop3_b32 v4, v4, v187, 15 bitop3:0x78
	v_lshlrev_b32_e32 v237, 4, v4
	v_add_u32_e32 v4, 8, v201
	v_bitop3_b32 v1, v1, v187, 15 bitop3:0x78
	v_bitop3_b32 v4, v4, v187, 15 bitop3:0x78
	v_bitop3_b32 v2, v2, v187, 15 bitop3:0x78
	v_lshlrev_b32_e32 v243, 4, v1
	v_add_u32_e32 v1, s42, v186
	v_lshlrev_b32_e32 v238, 4, v4
	v_add_u32_e32 v4, 10, v201
	v_lshlrev_b32_e32 v240, 4, v2
	v_bitop3_b32 v2, v3, v187, 15 bitop3:0x78
	s_lshl_b32 s58, s88, 7
	v_sub_u32_e32 v1, v1, v188
	v_bitop3_b32 v4, v4, v187, 15 bitop3:0x78
	v_lshlrev_b32_e32 v241, 4, v2
	v_bitop3_b32 v2, v201, v187, 15 bitop3:0x78
	v_subrev_u32_e32 v1, s58, v1
	v_mov_b32_e32 v14, v0
	v_mov_b32_e32 v15, v0
	v_lshlrev_b32_e32 v213, 7, v6
	v_lshlrev_b32_e32 v239, 4, v4
	v_lshlrev_b32_e32 v242, 4, v2
	s_add_i32 s9, s88, -1
	v_subrev_u32_e32 v244, s8, v1
	v_mov_b32_e32 v1, v0
	v_mov_b32_e32 v2, v0
	v_mov_b32_e32 v3, v0
	v_mov_b32_e32 v4, v0
	v_mov_b32_e32 v5, v0
	v_mov_b32_e32 v6, v0
	v_mov_b32_e32 v7, v0
	v_mov_b32_e32 v8, v0
	v_mov_b32_e32 v9, v0
	v_mov_b32_e32 v10, v0
	v_mov_b32_e32 v11, v0
	v_mov_b32_e32 v12, v0
	v_mov_b32_e32 v13, v0
	v_mov_b64_e32 v[30:31], v[14:15]
	v_mov_b64_e32 v[46:47], v[14:15]
	v_mov_b64_e32 v[62:63], v[14:15]
	v_mov_b64_e32 v[78:79], v[14:15]
	s_mov_b32 s56, 1
	s_mov_b32 s7, 0
	v_lshlrev_b32_e32 v169, 8, v186
	v_mul_f32_e32 v216, 0x80000000, v214
	v_mul_f32_e32 v217, -2.0, v214
	v_mul_f32_e32 v218, 0xc0400000, v214
	v_mul_f32_e32 v219, -4.0, v214
	v_mul_f32_e32 v220, 0xc0a00000, v214
	v_mul_f32_e32 v221, 0xc0c00000, v214
	v_mul_f32_e32 v222, 0xc0e00000, v214
	v_mul_f32_e32 v223, 0xc1800000, v214
	v_mul_f32_e32 v224, 0xc1880000, v214
	v_mul_f32_e32 v225, 0xc1900000, v214
	v_mul_f32_e32 v226, 0xc1980000, v214
	v_mul_f32_e32 v227, 0xc1a00000, v214
	v_mul_f32_e32 v228, 0xc1a80000, v214
	v_mul_f32_e32 v229, 0xc1b00000, v214
	v_mul_f32_e32 v230, 0xc1b80000, v214
	v_cmp_eq_u32_e64 s[40:41], 0, v187
	s_lshl_b32 s59, s88, 2
	v_mov_b32_e32 v245, 0
	v_mov_b32_e32 v246, 0xf149f2ca
	v_readlane_b32 s60, v254, 50
	v_readlane_b32 s61, v254, 38
	s_mov_b32 s88, s9
	v_mov_b64_e32 v[28:29], v[12:13]
	v_mov_b64_e32 v[26:27], v[10:11]
	v_mov_b64_e32 v[24:25], v[8:9]
	v_mov_b64_e32 v[22:23], v[6:7]
	v_mov_b64_e32 v[20:21], v[4:5]
	v_mov_b64_e32 v[18:19], v[2:3]
	v_mov_b64_e32 v[16:17], v[0:1]
	v_mov_b64_e32 v[44:45], v[12:13]
	v_mov_b64_e32 v[42:43], v[10:11]
	v_mov_b64_e32 v[40:41], v[8:9]
	v_mov_b64_e32 v[38:39], v[6:7]
	v_mov_b64_e32 v[36:37], v[4:5]
	v_mov_b64_e32 v[34:35], v[2:3]
	v_mov_b64_e32 v[32:33], v[0:1]
	v_mov_b64_e32 v[60:61], v[12:13]
	v_mov_b64_e32 v[58:59], v[10:11]
	v_mov_b64_e32 v[56:57], v[8:9]
	v_mov_b64_e32 v[54:55], v[6:7]
	v_mov_b64_e32 v[52:53], v[4:5]
	v_mov_b64_e32 v[50:51], v[2:3]
	v_mov_b64_e32 v[48:49], v[0:1]
	v_mov_b64_e32 v[76:77], v[12:13]
	v_mov_b64_e32 v[74:75], v[10:11]
	v_mov_b64_e32 v[72:73], v[8:9]
	v_mov_b64_e32 v[70:71], v[6:7]
	v_mov_b64_e32 v[68:69], v[4:5]
	v_mov_b64_e32 v[66:67], v[2:3]
	v_mov_b64_e32 v[64:65], v[0:1]
	s_waitcnt vmcnt(0) expcnt(0) lgkmcnt(0)
	s_barrier
	s_branch .LBB0_303
